# GEMM k-loops: next-B-slab DMA address arithmetic hoisted in front of the loop-head wait/barrier (fewer issue slots between barrier release and the fragment reads)
# baseline (speedup 1.0000x reference)
.Lg3_sw1:
	s_xor_b32 s23, s23, 0x4000
	s_add_u32 s72, s10, 0x10000
	s_addc_u32 s73, s11, 0
	s_add_u32 s84, s10, 0x20000
	s_addc_u32 s85, s11, 0
	s_add_u32 s90, s10, 0x30000
	s_addc_u32 s91, s11, 0
	s_add_u32 m0, s5, s23
	s_cmp_eq_u32 s16, 0
	s_waitcnt vmcnt(0)
	s_barrier
	s_cbranch_scc1 .Lg3_sw1_nb
	global_load_lds_dwordx4 v180, s[10:11]
	s_add_u32 m0, m0, 0x1000
	s_nop 0
	global_load_lds_dwordx4 v180, s[72:73]
	s_add_u32 m0, m0, 0x1000
	s_nop 0
	global_load_lds_dwordx4 v180, s[84:85]
	s_add_u32 m0, m0, 0x1000
	s_nop 0
	global_load_lds_dwordx4 v180, s[90:91]
	s_add_u32 s10, s10, 0x80
	s_addc_u32 s11, s11, 0

.Lg4_r1:
	s_xor_b32 s23, s23, 0x4000
	s_add_u32 s72, s10, 0x2c000
	s_addc_u32 s73, s11, 0
	s_add_u32 s84, s10, 0x58000
	s_addc_u32 s85, s11, 0
	s_add_u32 s90, s10, 0x84000
	s_addc_u32 s91, s11, 0
	s_add_u32 m0, s5, s23
	s_cmp_eq_u32 s16, 0
	s_waitcnt vmcnt(0)
	s_barrier
	s_cbranch_scc1 .Lg4_r1_nb
	global_load_lds_dwordx4 v180, s[10:11]
	s_add_u32 m0, m0, 0x1000
	s_nop 0
	global_load_lds_dwordx4 v180, s[72:73]
	s_add_u32 m0, m0, 0x1000
	s_nop 0
	global_load_lds_dwordx4 v180, s[84:85]
	s_add_u32 m0, m0, 0x1000
	s_nop 0
	global_load_lds_dwordx4 v180, s[90:91]
	s_add_u32 s10, s10, 0x80
	s_addc_u32 s11, s11, 0

.Lg4_pj:
	s_xor_b32 s16, s16, 0x4000
	s_add_u32 s72, s6, 0x10000
	s_addc_u32 s73, s7, 0
	s_add_u32 s84, s6, 0x20000
	s_addc_u32 s85, s7, 0
	s_add_u32 s90, s6, 0x30000
	s_addc_u32 s91, s7, 0
	s_add_u32 m0, s12, s16
	s_cmp_eq_u32 s15, 0
	s_waitcnt vmcnt(0)
	s_barrier
	s_cbranch_scc1 .Lg4_pj_nb
	global_load_lds_dwordx4 v180, s[6:7]
	s_add_u32 m0, m0, 0x1000
	s_nop 0
	global_load_lds_dwordx4 v180, s[72:73]
	s_add_u32 m0, m0, 0x1000
	s_nop 0
	global_load_lds_dwordx4 v180, s[84:85]
	s_add_u32 m0, m0, 0x1000
	s_nop 0
	global_load_lds_dwordx4 v180, s[90:91]
	s_add_u32 s6, s6, 0x80
	s_addc_u32 s7, s7, 0

.Lg3_sw2:
	s_xor_b32 s23, s23, 0x4000
	s_add_u32 s72, s8, 0x10000
	s_addc_u32 s73, s9, 0
	s_add_u32 s84, s8, 0x20000
	s_addc_u32 s85, s9, 0
	s_add_u32 s90, s8, 0x30000
	s_addc_u32 s91, s9, 0
	s_add_u32 m0, s5, s23
	s_cmp_eq_u32 s14, 0
	s_waitcnt vmcnt(0)
	s_barrier
	s_cbranch_scc1 .Lg3_sw2_nb
	global_load_lds_dwordx4 v180, s[8:9]
	s_add_u32 m0, m0, 0x1000
	s_nop 0
	global_load_lds_dwordx4 v180, s[72:73]
	s_add_u32 m0, m0, 0x1000
	s_nop 0
	global_load_lds_dwordx4 v180, s[84:85]
	s_add_u32 m0, m0, 0x1000
	s_nop 0
	global_load_lds_dwordx4 v180, s[90:91]
	s_add_u32 s8, s8, 0x80
	s_addc_u32 s9, s9, 0

.Lg4_r3:
	s_xor_b32 s23, s23, 0x4000
	s_add_u32 s72, s12, 0x2c000
	s_addc_u32 s73, s13, 0
	s_add_u32 s84, s12, 0x58000
	s_addc_u32 s85, s13, 0
	s_add_u32 s90, s12, 0x84000
	s_addc_u32 s91, s13, 0
	s_add_u32 m0, s5, s23
	s_cmp_eq_u32 s16, 0
	s_waitcnt vmcnt(0)
	s_barrier
	s_cbranch_scc1 .Lg4_r3_nb
	global_load_lds_dwordx4 v180, s[12:13]
	s_add_u32 m0, m0, 0x1000
	s_nop 0
	global_load_lds_dwordx4 v180, s[72:73]
	s_add_u32 m0, m0, 0x1000
	s_nop 0
	global_load_lds_dwordx4 v180, s[84:85]
	s_add_u32 m0, m0, 0x1000
	s_nop 0
	global_load_lds_dwordx4 v180, s[90:91]
	s_add_u32 s12, s12, 0x80
	s_addc_u32 s13, s13, 0
